# v43 + RWKV slot C: both MFMA pairs' LDS operand reads issued together (2 LDS round trips instead of 4 per chunk)
# speedup vs baseline: 1.0236x; 1.0015x over previous
; #define LAS __attribute__((address_space(3)))
; __device__ __forceinline__ bf16_t f2bf(float f) { const __bf16 r = (__bf16)f; bf16_t u; __builtin_memcpy(&u, &r, 2); return u; }
; __device__ __forceinline__ f32x4 mfma16(bf16x8 a, bf16x8 b, f32x4 c) { return __builtin_amdgcn_mfma_f32_16x16x32_bf16(a, b, c, 0, 0, 0); }
; __device__ __forceinline__ void rwkv_chunk_item(const P& p, const Ctx& c, int seg, int w, bool save) {
;     ...
;     auto gtile = [&](int pb, int l15, int quad) {
;         LAS bf16_t* EA = (LAS bf16_t*)(OB + pb * OPB + O_EA); LAS bf16_t* EB = (LAS bf16_t*)(OB + pb * OPB + O_EB);
;         LAS bf16_t* MT1 = (LAS bf16_t*)(OB + pb * OPB + O_MT1); LAS bf16_t* NT = (LAS bf16_t*)(OB + pb * OPB + O_NT); LAS float* MABT = (LAS float*)(OB + pb * OPB + O_MABT);
;         const int sb = c.wv >> 1, tb = c.wv & 1; f32x4 g = (f32x4){0.f, 0.f, 0.f, 0.f};
; #pragma unroll
;         for (int kk = 0; kk < 2; ++kk) g = mfma16(*(const LAS bf16x8*)(EB + (sb * 16 + l15) * 72 + kk * 32 + quad * 8), *(const LAS bf16x8*)(EA + (tb * 16 + l15) * 72 + kk * 32 + quad * 8), g);
; #pragma unroll
;         for (int jj = 0; jj < 4; ++jj) { const int s2 = quad * 4 + jj, tt = l15; const float v = g[jj];
;             if (tb == 0) { const float m = (s2 < tt) ? v : 0.f; if (sb == 0) { MABT[s2 * 20 + tt] = m; MT1[tt * 40 + s2] = 0; } else MT1[tt * 40 + 16 + s2] = f2bf(m); }
;             else { const float m = (s2 <= tt) ? v : 0.f; NT[tt * 40 + sb * 16 + s2] = f2bf(m); } } };
;     ...
; #pragma unroll
;         for (int x = 0; x < 2; ++x) { const int ti = c.wv * 2 + x, mt = ti >> 2, nt = ti & 3;
;             S[x] = mfma16(*(const LAS bf16x8*)(UV + (mt * 16 + l15) * 40 + quad * 8), *(const LAS bf16x8*)(EBT + (nt * 16 + l15) * 40 + quad * 8), S[x]);
;             const float gt = GT[nt * 16 + l15];
; #pragma unroll
;             for (int jj = 0; jj < 4; ++jj) S[x][jj] *= gt; }
;         simg(l15, quad);
;         if (c.wv < 4 && ch + 1 < SEGT / 16) gtile(pb ^ 1, l15, quad);
.LBB0_900:
	v_add_u32_e32 v22, s45, v82
	v_lshl_add_u32 v2, v45, 1, s88
	v_mad_u64_u32 v[22:23], s[2:3], v22, s64, v[2:3]
	ds_read_b128 v[22:25], v22 offset:14336
	v_add_u32_e32 v42, s34, v82
	v_mad_u64_u32 v[38:39], s[2:3], v42, s64, v[2:3]
	ds_read_b128 v[38:41], v38 offset:9216
	v_add_u32_e32 v124, s66, v82
	v_mad_u64_u32 v[124:125], s[2:3], v124, s64, v[2:3]
	ds_read_b128 v[124:127], v124 offset:9216
	v_lshl_add_u32 v128, v42, 2, s88
	v_add_u32_e32 v128, 0x5800, v128
	ds_read2_b32 v[42:43], v128 offset0:192 offset1:208
	s_waitcnt lgkmcnt(2)
	v_mfma_f32_16x16x32_bf16 v[6:9], v[22:25], v[38:41], v[6:9]
	s_waitcnt lgkmcnt(0)
	v_mfma_f32_16x16x32_bf16 v[10:13], v[22:25], v[124:127], v[10:13]
	v_mov_b32_e32 v2, v43
	v_lshlrev_b32_e32 v38, 2, v83
	s_nop 7
	v_pk_mul_f32 v[6:7], v[42:43], v[6:7] op_sel_hi:[0,1]
	s_nop 4
	v_pk_mul_f32 v[10:11], v[2:3], v[10:11] op_sel_hi:[0,1]
	v_pk_mul_f32 v[12:13], v[2:3], v[12:13] op_sel_hi:[0,1]
	v_add_u32_e32 v2, s45, v38
	v_lshlrev_b32_e32 v22, 1, v82
	v_mul_lo_u32 v2, v2, s63
	v_pk_mul_f32 v[8:9], v[42:43], v[8:9] op_sel_hi:[0,1]
	v_add3_u32 v2, s40, v22, v2
	v_cvt_pk_bf16_f32 v22, v7, s0
	ds_write_b16 v2, v22 offset:47248
	v_cvt_pk_bf16_f32 v22, v8, s0
	ds_write_b16 v2, v22 offset:47392
	v_cvt_pk_bf16_f32 v22, v9, s0
	ds_write_b16 v2, v22 offset:47536
	v_cvt_pk_bf16_f32 v22, v10, s0
	ds_write_b16 v2, v22 offset:47136
	v_cvt_pk_bf16_f32 v22, v11, s0
	ds_write_b16 v2, v22 offset:47280
	v_cvt_pk_bf16_f32 v22, v12, s0
	s_or_b64 s[2:3], s[56:57], s[4:5]
	v_cvt_pk_bf16_f32 v23, v6, s0
	ds_write_b16 v2, v22 offset:47424
	v_cvt_pk_bf16_f32 v22, v13, s0
	s_and_b64 vcc, exec, s[2:3]
	ds_write_b16 v2, v23 offset:47104
	ds_write_b16 v2, v22 offset:47568
	s_cbranch_vccnz .LBB0_929
	s_xor_b32 s2, s87, 1
	s_mulk_i32 s2, 0x5c00
	v_add_u32_e32 v2, s67, v82
	s_add_i32 s4, s2, 0
	v_mul_lo_u32 v2, v2, s63
	v_lshlrev_b32_e32 v22, 1, v45
	v_add_u32_e32 v23, s83, v82
	v_add3_u32 v2, s4, v2, v22
	v_mul_lo_u32 v23, v23, s63
	v_add3_u32 v39, s4, v23, v22
	ds_read_b128 v[22:25], v2 offset:4608
	ds_read_b128 v[40:43], v39
	ds_read_b128 v[124:127], v2 offset:4672
	ds_read_b128 v[86:89], v39 offset:64
	s_waitcnt lgkmcnt(2)
	v_mfma_f32_16x16x32_bf16 v[22:25], v[22:25], v[40:43], 0
	v_add_u32_e32 v39, s4, v84
	v_add_u32_e32 v2, s84, v39
	s_waitcnt lgkmcnt(0)
	v_mfma_f32_16x16x32_bf16 v[22:25], v[124:127], v[86:89], v[22:25]
	s_mov_b64 s[2:3], -1
	s_and_b64 vcc, exec, s[72:73]
	v_lshl_add_u32 v40, v38, 1, v2
	s_cbranch_vccz .LBB0_903
	s_nop 3
	v_cvt_pk_bf16_f32 v2, v22, s0
	v_cmp_le_i32_e32 vcc, v38, v82
	s_mov_b64 s[2:3], 0
	s_nop 0
	v_cndmask_b32_e32 v2, 0, v2, vcc
	ds_write_b16 v40, v2 offset:20736
